# loader waits no longer cover previous copy-out stores (31..18), peeled iteration stores moved after LDS writes
# speedup vs baseline: 1.0160x; 1.0070x over previous
; DI void gdn_scan(const Args& a, int l, int bh, LAS unsigned char* lds, const int tidx, const bool nostore) {
;     ...
;         bf16_t* obase = proj + ((size_t)b * SEQ + (pidx >> 4)) * NPROJ + C_GV + h * 128 + sub * 8;
.LBB0_363:
	s_add_u32 s6, s6, 0x2a000
	s_addc_u32 s7, s7, 0
	v_lshl_add_u64 v[56:57], s[6:7], 0, v[114:115]
	v_lshl_add_u64 v[60:61], s[6:7], 0, v[116:117]
	v_lshl_add_u64 v[64:65], s[6:7], 0, v[118:119]
	v_lshl_add_u64 v[68:69], s[6:7], 0, v[120:121]
	v_lshl_add_u64 v[72:73], s[6:7], 0, v[122:123]
	v_lshl_add_u64 v[76:77], s[6:7], 0, v[124:125]
	v_lshl_add_u64 v[80:81], s[6:7], 0, v[126:127]
	v_lshl_add_u64 v[84:85], s[6:7], 0, v[128:129]
	v_lshl_add_u64 v[88:89], s[6:7], 0, v[130:131]
	v_lshl_add_u64 v[92:93], s[6:7], 0, v[132:133]
	v_lshl_add_u64 v[96:97], s[6:7], 0, v[134:135]
	v_lshl_add_u64 v[100:101], s[6:7], 0, v[136:137]
	v_lshl_add_u64 v[104:105], s[6:7], 0, v[138:139]
	v_lshl_add_u64 v[108:109], s[6:7], 0, v[140:141]
	global_load_dwordx4 v[56:59], v[56:57], off
	s_nop 0
	global_load_dwordx4 v[60:63], v[60:61], off
	s_nop 0
	global_load_dwordx4 v[64:67], v[64:65], off
	s_nop 0
	global_load_dwordx4 v[68:71], v[68:69], off
	s_nop 0
	global_load_dwordx4 v[72:75], v[72:73], off
	s_nop 0
	global_load_dwordx4 v[76:79], v[76:77], off
	s_nop 0
	global_load_dwordx4 v[80:83], v[80:81], off
	s_nop 0
	global_load_dwordx4 v[84:87], v[84:85], off
	s_nop 0
	global_load_dwordx4 v[88:91], v[88:89], off
	s_nop 0
	global_load_dwordx4 v[92:95], v[92:93], off
	s_nop 0
	global_load_dwordx4 v[96:99], v[96:97], off
	s_nop 0
	global_load_dwordx4 v[100:103], v[100:101], off
	s_nop 0
	global_load_dwordx4 v[104:107], v[104:105], off
	s_nop 0
	global_load_dwordx4 v[108:111], v[108:109], off
	s_add_u32 s6, s42, s13
	v_readlane_b32 s5, v254, 29
	s_addc_u32 s7, s43, s12
	v_lshl_add_u64 v[114:115], s[6:7], 0, v[114:115]
	v_lshl_add_u32 v144, v143, 1, s5
	v_lshl_add_u64 v[116:117], s[6:7], 0, v[116:117]
	v_lshl_add_u64 v[118:119], s[6:7], 0, v[118:119]
	v_lshl_add_u64 v[120:121], s[6:7], 0, v[120:121]
	v_lshl_add_u64 v[122:123], s[6:7], 0, v[122:123]
	v_lshl_add_u64 v[124:125], s[6:7], 0, v[124:125]
	v_lshl_add_u64 v[126:127], s[6:7], 0, v[126:127]
	v_lshl_add_u64 v[128:129], s[6:7], 0, v[128:129]
	v_lshl_add_u64 v[130:131], s[6:7], 0, v[130:131]
	v_lshl_add_u64 v[132:133], s[6:7], 0, v[132:133]
	v_lshl_add_u64 v[134:135], s[6:7], 0, v[134:135]
	v_lshl_add_u64 v[136:137], s[6:7], 0, v[136:137]
	v_lshl_add_u64 v[138:139], s[6:7], 0, v[138:139]
	v_lshl_add_u64 v[140:141], s[6:7], 0, v[140:141]
	v_mad_i64_i32 v[142:143], s[6:7], v142, s47, 0
	v_mad_i64_i32 v[142:143], s[4:5], s4, v243, v[142:143]
	s_waitcnt vmcnt(27)
	ds_write_b128 v174, v[0:3]
	s_waitcnt vmcnt(26)
	ds_write_b128 v174, v[4:7] offset:4096
	s_waitcnt vmcnt(25)
	ds_write_b128 v174, v[8:11] offset:8192
	s_waitcnt vmcnt(24)
	ds_write_b128 v174, v[12:15] offset:12288
	s_waitcnt vmcnt(23)
	ds_write_b128 v174, v[16:19] offset:16384
	s_waitcnt vmcnt(22)
	ds_write_b128 v174, v[20:23] offset:20480
	s_waitcnt vmcnt(21)
	ds_write_b128 v174, v[24:27] offset:24576
	s_waitcnt vmcnt(20)
	ds_write_b128 v174, v[28:31] offset:28672
	s_waitcnt vmcnt(19)
	ds_write_b128 v174, v[32:35] offset:32768
	s_waitcnt vmcnt(18)
	ds_write_b128 v174, v[36:39] offset:36864
	s_waitcnt vmcnt(17)
	ds_write_b128 v174, v[40:43] offset:40960
	s_waitcnt vmcnt(16)
	ds_write_b128 v174, v[44:47] offset:45056
	s_waitcnt vmcnt(15)
	ds_write_b128 v174, v[48:51] offset:49152
	s_waitcnt vmcnt(14)
	ds_write_b128 v174, v[52:55] offset:53248
	s_and_b64 vcc, exec, s[0:1]
	s_cbranch_vccnz .Lldr_p1_st_done
	ds_read_b128 v[180:183], v177
	v_add_co_u32_e32 v184, vcc, 0x36000, v112
	s_waitcnt lgkmcnt(0)
	global_store_dwordx4 v[112:113], v[180:183], off
	ds_read_b128 v[180:183], v177 offset:4352
	v_addc_co_u32_e32 v185, vcc, 0, v113, vcc
	s_waitcnt lgkmcnt(0)
	global_store_dwordx4 v[184:185], v[180:183], off
	ds_read_b128 v[180:183], v177 offset:8704
	v_add_co_u32_e32 v184, vcc, 0x6c000, v112
	s_nop 1
	v_addc_co_u32_e32 v185, vcc, 0, v113, vcc
	s_waitcnt lgkmcnt(0)
	global_store_dwordx4 v[184:185], v[180:183], off
	ds_read_b128 v[180:183], v177 offset:13056
	v_add_co_u32_e32 v184, vcc, 0xa2000, v112
	s_nop 1
	v_addc_co_u32_e32 v185, vcc, 0, v113, vcc
	s_waitcnt lgkmcnt(0)
	global_store_dwordx4 v[184:185], v[180:183], off
.Lldr_p1_st_done:
	s_lshl_b64 s[4:5], s[8:9], 1
	s_waitcnt lgkmcnt(0)
	s_barrier
	v_and_b32_e32 v145, 15, v220
	s_add_u32 s4, s42, s4
	v_lshl_or_b32 v142, v145, 4, v142
	s_addc_u32 s5, s43, s5
	v_lshl_add_u64 v[142:143], s[4:5], 0, v[142:143]
	s_mov_b32 s6, 2
	v_add_u32_e32 v178, v144, v176
	s_branch .LBB0_365

; DI void gdn_scan(const Args& a, int l, int bh, LAS unsigned char* lds, const int tidx, const bool nostore) {
;     ...
;         for (int n2 = 0; n2 < 64; n2 += 2) {
;             LOADER_ITER(n2, pfa, pfb);
;             LOADER_ITER(n2 + 1, pfb, pfa);
.LBB0_367:
	s_cmp_gt_u32 s6, 61
	s_cselect_b64 s[4:5], -1, 0
	s_and_b64 vcc, exec, s[4:5]
	v_lshl_add_u64 v[172:173], v[114:115], 0, s[94:95]
	v_lshl_add_u64 v[170:171], v[116:117], 0, s[94:95]
	v_lshl_add_u64 v[168:169], v[118:119], 0, s[94:95]
	v_lshl_add_u64 v[166:167], v[120:121], 0, s[94:95]
	v_lshl_add_u64 v[164:165], v[122:123], 0, s[94:95]
	v_lshl_add_u64 v[160:161], v[124:125], 0, s[94:95]
	v_lshl_add_u64 v[158:159], v[126:127], 0, s[94:95]
	v_lshl_add_u64 v[156:157], v[128:129], 0, s[94:95]
	v_lshl_add_u64 v[154:155], v[130:131], 0, s[94:95]
	v_lshl_add_u64 v[152:153], v[132:133], 0, s[94:95]
	v_lshl_add_u64 v[150:151], v[134:135], 0, s[94:95]
	v_lshl_add_u64 v[148:149], v[136:137], 0, s[94:95]
	v_lshl_add_u64 v[146:147], v[138:139], 0, s[94:95]
	v_lshl_add_u64 v[144:145], v[140:141], 0, s[94:95]
	s_cbranch_vccnz .LBB0_369
	v_add_co_u32_e32 v0, vcc, 0x15538000, v172
	s_nop 1
	v_addc_co_u32_e32 v1, vcc, 0, v173, vcc
	v_add_co_u32_e32 v4, vcc, 0x15538000, v170
	global_load_dwordx4 v[0:3], v[0:1], off
	s_nop 0
	v_addc_co_u32_e32 v5, vcc, 0, v171, vcc
	v_add_co_u32_e32 v8, vcc, 0x15538000, v168
	global_load_dwordx4 v[4:7], v[4:5], off
	s_nop 0
	v_addc_co_u32_e32 v9, vcc, 0, v169, vcc
	v_add_co_u32_e32 v12, vcc, 0x15538000, v166
	global_load_dwordx4 v[8:11], v[8:9], off
	s_nop 0
	v_addc_co_u32_e32 v13, vcc, 0, v167, vcc
	v_add_co_u32_e32 v16, vcc, 0x15538000, v164
	global_load_dwordx4 v[12:15], v[12:13], off
	s_nop 0
	v_addc_co_u32_e32 v17, vcc, 0, v165, vcc
	v_add_co_u32_e32 v20, vcc, 0x15538000, v160
	global_load_dwordx4 v[16:19], v[16:17], off
	s_nop 0
	v_addc_co_u32_e32 v21, vcc, 0, v161, vcc
	v_add_co_u32_e32 v24, vcc, 0x15538000, v158
	global_load_dwordx4 v[20:23], v[20:21], off
	s_nop 0
	v_addc_co_u32_e32 v25, vcc, 0, v159, vcc
	v_add_co_u32_e32 v28, vcc, 0x15538000, v156
	global_load_dwordx4 v[24:27], v[24:25], off
	s_nop 0
	v_addc_co_u32_e32 v29, vcc, 0, v157, vcc
	v_add_co_u32_e32 v32, vcc, 0x15538000, v154
	global_load_dwordx4 v[28:31], v[28:29], off
	s_nop 0
	v_addc_co_u32_e32 v33, vcc, 0, v155, vcc
	v_add_co_u32_e32 v36, vcc, 0x15538000, v152
	global_load_dwordx4 v[32:35], v[32:33], off
	s_nop 0
	v_addc_co_u32_e32 v37, vcc, 0, v153, vcc
	v_add_co_u32_e32 v40, vcc, 0x15538000, v150
	global_load_dwordx4 v[36:39], v[36:37], off
	s_nop 0
	v_addc_co_u32_e32 v41, vcc, 0, v151, vcc
	v_add_co_u32_e32 v44, vcc, 0x15538000, v148
	global_load_dwordx4 v[40:43], v[40:41], off
	s_nop 0
	v_addc_co_u32_e32 v45, vcc, 0, v149, vcc
	v_add_co_u32_e32 v48, vcc, 0x15538000, v146
	global_load_dwordx4 v[44:47], v[44:45], off
	s_nop 0
	v_addc_co_u32_e32 v49, vcc, 0, v147, vcc
	v_add_co_u32_e32 v52, vcc, 0x15538000, v144
	global_load_dwordx4 v[48:51], v[48:49], off
	s_nop 0
	v_addc_co_u32_e32 v53, vcc, 0, v145, vcc
	global_load_dwordx4 v[52:55], v[52:53], off
	s_and_b64 vcc, exec, s[0:1]
	s_cbranch_vccnz .Lldr_even_A27
	s_waitcnt vmcnt(31)
	ds_write_b128 v174, v[56:59] offset:57344
	s_waitcnt vmcnt(30)
	ds_write_b128 v174, v[60:63] offset:61440
	s_waitcnt vmcnt(29)
	ds_write_b128 v175, v[64:67] offset:8192
	s_waitcnt vmcnt(28)
	ds_write_b128 v175, v[68:71] offset:12288
	s_waitcnt vmcnt(27)
	ds_write_b128 v175, v[72:75] offset:16384
	s_waitcnt vmcnt(26)
	ds_write_b128 v175, v[76:79] offset:20480
	s_waitcnt vmcnt(25)
	ds_write_b128 v175, v[80:83] offset:24576
	s_waitcnt vmcnt(24)
	ds_write_b128 v175, v[84:87] offset:28672
	s_waitcnt vmcnt(23)
	ds_write_b128 v175, v[88:91] offset:32768
	s_waitcnt vmcnt(22)
	ds_write_b128 v175, v[92:95] offset:36864
	s_waitcnt vmcnt(21)
	ds_write_b128 v175, v[96:99] offset:40960
	s_waitcnt vmcnt(20)
	ds_write_b128 v175, v[100:103] offset:45056
	s_waitcnt vmcnt(19)
	ds_write_b128 v175, v[104:107] offset:49152
	s_waitcnt vmcnt(18)
	ds_write_b128 v175, v[108:111] offset:53248
	s_branch .Lldr_even_wr_done
.Lldr_even_A27:
	s_waitcnt vmcnt(27)
	ds_write_b128 v174, v[56:59] offset:57344
	s_waitcnt vmcnt(26)
	ds_write_b128 v174, v[60:63] offset:61440
	s_waitcnt vmcnt(25)
	ds_write_b128 v175, v[64:67] offset:8192
	s_waitcnt vmcnt(24)
	ds_write_b128 v175, v[68:71] offset:12288
	s_waitcnt vmcnt(23)
	ds_write_b128 v175, v[72:75] offset:16384
	s_waitcnt vmcnt(22)
	ds_write_b128 v175, v[76:79] offset:20480
	s_waitcnt vmcnt(21)
	ds_write_b128 v175, v[80:83] offset:24576
	s_waitcnt vmcnt(20)
	ds_write_b128 v175, v[84:87] offset:28672
	s_waitcnt vmcnt(19)
	ds_write_b128 v175, v[88:91] offset:32768
	s_waitcnt vmcnt(18)
	ds_write_b128 v175, v[92:95] offset:36864
	s_waitcnt vmcnt(17)
	ds_write_b128 v175, v[96:99] offset:40960
	s_waitcnt vmcnt(16)
	ds_write_b128 v175, v[100:103] offset:45056
	s_waitcnt vmcnt(15)
	ds_write_b128 v175, v[104:107] offset:49152
	s_waitcnt vmcnt(14)
	ds_write_b128 v175, v[108:111] offset:53248
	s_branch .Lldr_even_wr_done

; DI void gdn_scan(const Args& a, int l, int bh, LAS unsigned char* lds, const int tidx, const bool nostore) {
;     ...
;         for (int n2 = 0; n2 < 64; n2 += 2) {
;             LOADER_ITER(n2, pfa, pfb);
;             LOADER_ITER(n2 + 1, pfb, pfa);
.LBB0_373:
	v_add_co_u32_e32 v56, vcc, 0x15546000, v172
	s_nop 1
	v_addc_co_u32_e32 v57, vcc, 0, v173, vcc
	v_add_co_u32_e32 v60, vcc, 0x15546000, v170
	global_load_dwordx4 v[56:59], v[56:57], off
	s_nop 0
	v_addc_co_u32_e32 v61, vcc, 0, v171, vcc
	v_add_co_u32_e32 v64, vcc, 0x15546000, v168
	global_load_dwordx4 v[60:63], v[60:61], off
	s_nop 0
	v_addc_co_u32_e32 v65, vcc, 0, v169, vcc
	v_add_co_u32_e32 v68, vcc, 0x15546000, v166
	global_load_dwordx4 v[64:67], v[64:65], off
	s_nop 0
	v_addc_co_u32_e32 v69, vcc, 0, v167, vcc
	v_add_co_u32_e32 v72, vcc, 0x15546000, v164
	global_load_dwordx4 v[68:71], v[68:69], off
	s_nop 0
	v_addc_co_u32_e32 v73, vcc, 0, v165, vcc
	v_add_co_u32_e32 v76, vcc, 0x15546000, v160
	global_load_dwordx4 v[72:75], v[72:73], off
	s_nop 0
	v_addc_co_u32_e32 v77, vcc, 0, v161, vcc
	v_add_co_u32_e32 v80, vcc, 0x15546000, v158
	global_load_dwordx4 v[76:79], v[76:77], off
	s_nop 0
	v_addc_co_u32_e32 v81, vcc, 0, v159, vcc
	v_add_co_u32_e32 v84, vcc, 0x15546000, v156
	global_load_dwordx4 v[80:83], v[80:81], off
	s_nop 0
	v_addc_co_u32_e32 v85, vcc, 0, v157, vcc
	v_add_co_u32_e32 v88, vcc, 0x15546000, v154
	global_load_dwordx4 v[84:87], v[84:85], off
	s_nop 0
	v_addc_co_u32_e32 v89, vcc, 0, v155, vcc
	v_add_co_u32_e32 v92, vcc, 0x15546000, v152
	global_load_dwordx4 v[88:91], v[88:89], off
	s_nop 0
	v_addc_co_u32_e32 v93, vcc, 0, v153, vcc
	v_add_co_u32_e32 v96, vcc, 0x15546000, v150
	global_load_dwordx4 v[92:95], v[92:93], off
	s_nop 0
	v_addc_co_u32_e32 v97, vcc, 0, v151, vcc
	v_add_co_u32_e32 v100, vcc, 0x15546000, v148
	global_load_dwordx4 v[96:99], v[96:97], off
	s_nop 0
	v_addc_co_u32_e32 v101, vcc, 0, v149, vcc
	v_add_co_u32_e32 v104, vcc, 0x15546000, v146
	global_load_dwordx4 v[100:103], v[100:101], off
	s_nop 0
	v_addc_co_u32_e32 v105, vcc, 0, v147, vcc
	v_add_co_u32_e32 v108, vcc, 0x15546000, v144
	global_load_dwordx4 v[104:107], v[104:105], off
	s_nop 0
	v_addc_co_u32_e32 v109, vcc, 0, v145, vcc
	global_load_dwordx4 v[108:111], v[108:109], off
	s_and_b64 vcc, exec, s[0:1]
	s_cbranch_vccnz .Lldr_odd_A27
	s_waitcnt vmcnt(31)
	ds_write_b128 v174, v[0:3]
	s_waitcnt vmcnt(30)
	ds_write_b128 v174, v[4:7] offset:4096
	s_waitcnt vmcnt(29)
	ds_write_b128 v174, v[8:11] offset:8192
	s_waitcnt vmcnt(28)
	ds_write_b128 v174, v[12:15] offset:12288
	s_waitcnt vmcnt(27)
	ds_write_b128 v174, v[16:19] offset:16384
	s_waitcnt vmcnt(26)
	ds_write_b128 v174, v[20:23] offset:20480
	s_waitcnt vmcnt(25)
	ds_write_b128 v174, v[24:27] offset:24576
	s_waitcnt vmcnt(24)
	ds_write_b128 v174, v[28:31] offset:28672
	s_waitcnt vmcnt(23)
	ds_write_b128 v174, v[32:35] offset:32768
	s_waitcnt vmcnt(22)
	ds_write_b128 v174, v[36:39] offset:36864
	s_waitcnt vmcnt(21)
	ds_write_b128 v174, v[40:43] offset:40960
	s_waitcnt vmcnt(20)
	ds_write_b128 v174, v[44:47] offset:45056
	s_waitcnt vmcnt(19)
	ds_write_b128 v174, v[48:51] offset:49152
	s_waitcnt vmcnt(18)
	ds_write_b128 v174, v[52:55] offset:53248
	s_branch .Lldr_odd_wr_done
.Lldr_odd_A27:
	s_waitcnt vmcnt(27)
	ds_write_b128 v174, v[0:3]
	s_waitcnt vmcnt(26)
	ds_write_b128 v174, v[4:7] offset:4096
	s_waitcnt vmcnt(25)
	ds_write_b128 v174, v[8:11] offset:8192
	s_waitcnt vmcnt(24)
	ds_write_b128 v174, v[12:15] offset:12288
	s_waitcnt vmcnt(23)
	ds_write_b128 v174, v[16:19] offset:16384
	s_waitcnt vmcnt(22)
	ds_write_b128 v174, v[20:23] offset:20480
	s_waitcnt vmcnt(21)
	ds_write_b128 v174, v[24:27] offset:24576
	s_waitcnt vmcnt(20)
	ds_write_b128 v174, v[28:31] offset:28672
	s_waitcnt vmcnt(19)
	ds_write_b128 v174, v[32:35] offset:32768
	s_waitcnt vmcnt(18)
	ds_write_b128 v174, v[36:39] offset:36864
	s_waitcnt vmcnt(17)
	ds_write_b128 v174, v[40:43] offset:40960
	s_waitcnt vmcnt(16)
	ds_write_b128 v174, v[44:47] offset:45056
	s_waitcnt vmcnt(15)
	ds_write_b128 v174, v[48:51] offset:49152
	s_waitcnt vmcnt(14)
	ds_write_b128 v174, v[52:55] offset:53248
